# GLA chunk prefetch: 27 ushort loads use SGPR-base + pre-doubled 32-bit VGPR offsets (kept in the former zero high halves) instead of a 64-bit VALU add per load
# speedup vs baseline: 1.0446x; 1.0021x over previous
.LBB0_533:
	s_or_b64 exec, exec, s[10:11]
	v_cmp_gt_i32_e32 vcc, 64, v2
	v_lshlrev_b32_e32 v129, 2, v2
	s_and_saveexec_b64 s[10:11], vcc
	ds_write_b32 v129, v179 offset:23552
	s_or_b64 exec, exec, s[10:11]
	s_add_u32 s58, s2, 0x22622100
	s_addc_u32 s59, s3, 0
	s_ashr_i32 s54, s95, 2
	v_lshlrev_b32_e32 v25, 3, v8
	s_add_u32 s56, s2, 0x18e80000
	v_and_b32_e32 v3, 24, v25
	s_addc_u32 s57, s3, 0
	s_ashr_i32 s55, s54, 31
	v_mul_u32_u24_e32 v3, 0x480, v3
	s_mul_i32 s10, s54, 0x480000
	v_add3_u32 v178, v0, s5, v3
	s_mul_hi_i32 s5, s54, 0x480000
	s_add_u32 s12, s58, s10
	s_addc_u32 s13, s59, s5
	v_lshl_add_u64 v[4:5], v[178:179], 1, s[12:13]
	v_add_u32_e32 v72, 0xc0, v178
	v_mov_b32_e32 v73, v179
	v_add_u32_e32 v74, 0x480, v178
	v_mov_b32_e32 v75, v179
	v_add_u32_e32 v76, 0x540, v178
	v_mov_b32_e32 v77, v179
	v_add_u32_e32 v78, 0x900, v178
	v_mov_b32_e32 v79, v179
	v_add_u32_e32 v80, 0x9c0, v178
	v_mov_b32_e32 v81, v179
	v_add_u32_e32 v82, 0xd80, v178
	v_mov_b32_e32 v83, v179
	v_add_u32_e32 v84, 0xe40, v178
	v_mov_b32_e32 v85, v179
	v_add_u32_e32 v86, 0x1200, v178
	v_mov_b32_e32 v87, v179
	v_mul_hi_u32 v3, v2, s87
	v_lshl_add_u64 v[6:7], v[72:73], 1, s[12:13]
	v_lshl_add_u64 v[12:13], v[74:75], 1, s[12:13]
	v_lshl_add_u64 v[14:15], v[76:77], 1, s[12:13]
	v_lshl_add_u64 v[16:17], v[78:79], 1, s[12:13]
	v_lshl_add_u64 v[18:19], v[80:81], 1, s[12:13]
	v_lshl_add_u64 v[20:21], v[82:83], 1, s[12:13]
	v_lshl_add_u64 v[22:23], v[84:85], 1, s[12:13]
	global_load_ushort v26, v[4:5], off
	global_load_ushort v143, v[6:7], off
	global_load_ushort v27, v[12:13], off
	global_load_ushort v140, v[14:15], off
	global_load_ushort v28, v[16:17], off
	global_load_ushort v136, v[18:19], off
	global_load_ushort v29, v[20:21], off
	global_load_ushort v138, v[22:23], off
	v_lshl_add_u64 v[4:5], v[86:87], 1, s[12:13]
	v_add_u32_e32 v88, 0x12c0, v178
	v_mov_b32_e32 v89, v179
	v_add_u32_e32 v90, 0x1680, v178
	v_mov_b32_e32 v91, v179
	v_add_u32_e32 v92, 0x1740, v178
	v_mov_b32_e32 v93, v179
	v_add_u32_e32 v94, 0x1b00, v178
	v_mov_b32_e32 v95, v179
	v_add_u32_e32 v96, 0x1bc0, v178
	v_mov_b32_e32 v97, v179
	v_add_u32_e32 v98, 0x1f80, v178
	v_mov_b32_e32 v99, v179
	v_add_u32_e32 v100, 0x2040, v178
	v_mov_b32_e32 v101, v179
	v_lshrrev_b32_e32 v3, 6, v3
	v_lshl_add_u64 v[6:7], v[88:89], 1, s[12:13]
	v_lshl_add_u64 v[12:13], v[90:91], 1, s[12:13]
	v_lshl_add_u64 v[14:15], v[92:93], 1, s[12:13]
	v_lshl_add_u64 v[16:17], v[94:95], 1, s[12:13]
	v_lshl_add_u64 v[18:19], v[96:97], 1, s[12:13]
	v_lshl_add_u64 v[20:21], v[98:99], 1, s[12:13]
	v_lshl_add_u64 v[22:23], v[100:101], 1, s[12:13]
	global_load_ushort v30, v[4:5], off
	global_load_ushort v144, v[6:7], off
	global_load_ushort v31, v[12:13], off
	global_load_ushort v142, v[14:15], off
	global_load_ushort v32, v[16:17], off
	global_load_ushort v137, v[18:19], off
	global_load_ushort v33, v[20:21], off
	global_load_ushort v139, v[22:23], off
	s_mul_i32 s5, s4, 0x60
	v_mul_lo_u32 v4, v3, s86
	v_mul_lo_u32 v3, v3, s75
	s_addk_i32 s5, 0x180
	v_sub_u32_e32 v3, v2, v3
	v_add_u32_e32 v34, 0x100, v2
	v_add3_u32 v102, v3, s5, v4
	v_mul_hi_u32 v3, v34, s87
	v_lshrrev_b32_e32 v3, 6, v3
	v_mul_lo_u32 v6, v3, s86
	v_mul_lo_u32 v3, v3, s75
	v_sub_u32_e32 v3, v34, v3
	v_add_u32_e32 v35, 0x200, v2
	v_add3_u32 v104, v3, s5, v6
	v_mul_hi_u32 v3, v35, s87
	v_lshrrev_b32_e32 v3, 6, v3
	v_mul_lo_u32 v12, v3, s86
	v_mul_lo_u32 v3, v3, s75
	v_sub_u32_e32 v3, v35, v3
	v_add_u32_e32 v36, 0x300, v2
	v_add3_u32 v106, v3, s5, v12
	v_mul_hi_u32 v3, v36, s87
	v_lshrrev_b32_e32 v3, 6, v3
	v_mul_lo_u32 v14, v3, s86
	v_mul_lo_u32 v3, v3, s75
	v_sub_u32_e32 v3, v36, v3
	v_add_u32_e32 v37, 0x400, v2
	v_add3_u32 v108, v3, s5, v14
	v_mul_hi_u32 v3, v37, s87
	v_lshrrev_b32_e32 v3, 6, v3
	v_mul_lo_u32 v16, v3, s86
	v_mul_lo_u32 v3, v3, s75
	v_sub_u32_e32 v3, v37, v3
	v_add_u32_e32 v38, 0x500, v2
	v_add3_u32 v110, v3, s5, v16
	v_mul_hi_u32 v3, v38, s87
	v_lshrrev_b32_e32 v3, 6, v3
	v_mul_lo_u32 v18, v3, s86
	v_mul_lo_u32 v3, v3, s75
	v_sub_u32_e32 v3, v38, v3
	v_add_u32_e32 v39, 0x600, v2
	v_add3_u32 v112, v3, s5, v18
	v_mul_hi_u32 v3, v39, s87
	v_lshrrev_b32_e32 v3, 6, v3
	v_mul_lo_u32 v20, v3, s86
	v_mul_lo_u32 v3, v3, s75
	v_sub_u32_e32 v3, v39, v3
	v_add_u32_e32 v40, 0x700, v2
	v_add3_u32 v114, v3, s5, v20
	v_mul_hi_u32 v3, v40, s87
	v_lshrrev_b32_e32 v3, 6, v3
	v_mul_lo_u32 v22, v3, s86
	v_mul_lo_u32 v3, v3, s75
	v_mov_b32_e32 v103, v179
	v_mov_b32_e32 v111, v179
	v_sub_u32_e32 v3, v40, v3
	v_lshl_add_u64 v[4:5], v[102:103], 1, s[12:13]
	v_mov_b32_e32 v105, v179
	v_mov_b32_e32 v107, v179
	v_mov_b32_e32 v109, v179
	v_lshl_add_u64 v[16:17], v[110:111], 1, s[12:13]
	v_mov_b32_e32 v113, v179
	v_mov_b32_e32 v115, v179
	v_add3_u32 v116, v3, s5, v22
	v_mov_b32_e32 v117, v179
	v_lshl_add_u64 v[6:7], v[104:105], 1, s[12:13]
	v_lshl_add_u64 v[12:13], v[106:107], 1, s[12:13]
	v_lshl_add_u64 v[14:15], v[108:109], 1, s[12:13]
	v_lshl_add_u64 v[18:19], v[112:113], 1, s[12:13]
	v_lshl_add_u64 v[20:21], v[114:115], 1, s[12:13]
	v_lshl_add_u64 v[22:23], v[116:117], 1, s[12:13]
	global_load_ushort v181, v[4:5], off
	global_load_ushort v182, v[6:7], off
	global_load_ushort v183, v[12:13], off
	global_load_ushort v184, v[14:15], off
	global_load_ushort v185, v[16:17], off
	global_load_ushort v186, v[18:19], off
	global_load_ushort v187, v[20:21], off
	global_load_ushort v188, v[22:23], off
	v_add_u32_e32 v16, 0x800, v2
	v_mul_hi_u32 v3, v16, s87
	v_lshrrev_b32_e32 v3, 6, v3
	v_mul_lo_u32 v4, v3, s86
	v_mul_lo_u32 v3, v3, s75
	v_sub_u32_e32 v3, v16, v3
	v_add_u32_e32 v17, 0x900, v2
	v_add3_u32 v118, v3, s5, v4
	v_mul_hi_u32 v3, v17, s87
	v_lshrrev_b32_e32 v3, 6, v3
	v_mul_lo_u32 v6, v3, s86
	v_mul_lo_u32 v3, v3, s75
	v_sub_u32_e32 v3, v17, v3
	v_add_u32_e32 v18, 0xa00, v2
	v_add3_u32 v120, v3, s5, v6
	v_mul_hi_u32 v3, v18, s87
	v_lshrrev_b32_e32 v3, 6, v3
	v_mul_lo_u32 v12, v3, s86
	v_mul_lo_u32 v3, v3, s75
	v_sub_u32_e32 v3, v18, v3
	v_add_u32_e32 v19, 0xb00, v2
	v_add3_u32 v122, v3, s5, v12
	v_mul_hi_u32 v3, v19, s87
	v_lshrrev_b32_e32 v3, 6, v3
	v_mul_lo_u32 v14, v3, s86
	v_mul_lo_u32 v3, v3, s75
	s_lshl_b64 s[10:11], s[54:55], 17
	s_lshl_b64 s[52:53], s[54:55], 11
	v_mov_b32_e32 v119, v179
	v_sub_u32_e32 v3, v19, v3
	v_lshl_add_u64 v[4:5], v[118:119], 1, s[12:13]
	v_mov_b32_e32 v121, v179
	v_mov_b32_e32 v123, v179
	v_add3_u32 v124, v3, s5, v14
	v_mov_b32_e32 v125, v179
	s_add_u32 s10, s56, s10
	v_ashrrev_i32_e32 v3, 31, v2
	v_lshl_add_u64 v[6:7], v[120:121], 1, s[12:13]
	v_lshl_add_u64 v[12:13], v[122:123], 1, s[12:13]
	v_lshl_add_u64 v[14:15], v[124:125], 1, s[12:13]
	global_load_ushort v189, v[4:5], off
	global_load_ushort v190, v[6:7], off
	global_load_ushort v191, v[12:13], off
	global_load_ushort v192, v[14:15], off
	s_addc_u32 s11, s57, s11
	v_lshlrev_b64 v[4:5], 2, v[2:3]
	v_add_u32_e32 v3, 47, v2
	v_lshl_add_u64 v[6:7], s[10:11], 0, v[4:5]
	v_lshlrev_b32_e32 v126, 2, v0
	v_cmp_gt_u32_e64 s[16:17], s67, v3
	v_and_b32_e32 v3, 0x7ffffff3, v0
	v_and_b32_e32 v1, 31, v2
	v_bfe_u32 v11, v2, 5, 1
	global_load_dword v193, v[6:7], off
	global_load_dword v194, v[6:7], off offset:1024
	v_and_b32_e32 v6, 16, v126
	v_lshlrev_b32_e32 v3, 1, v3
	v_and_b32_e32 v7, 8, v0
	v_ashrrev_i32_e32 v24, 6, v2
	s_movk_i32 s5, 0x8f
	v_or3_b32 v3, v6, v3, v7
	v_mul_u32_u24_e32 v6, 56, v1
	v_lshlrev_b32_e32 v128, 4, v11
	v_cmp_lt_i32_e64 s[14:15], s5, v2
	s_movk_i32 s5, 0x4c
	v_lshl_add_u32 v145, v6, 1, v128
	v_lshlrev_b32_e32 v6, 5, v24
	v_ashrrev_i32_e32 v9, 4, v9
	s_waitcnt vmcnt(30)
	v_mad_u64_u32 v[12:13], s[18:19], v0, s5, v[126:127]
	v_or_b32_e32 v7, v6, v1
	v_add_u32_e32 v9, v9, v10
	v_mad_u64_u32 v[130:131], s[18:19], v7, s74, v[128:129]
	v_lshlrev_b32_e32 v13, 5, v1
	v_mul_lo_u32 v10, v9, s75
	v_cmp_lt_i32_e64 s[10:11], 47, v2
	v_cmp_lt_i32_e64 s[12:13], s67, v2
	v_sub_u32_e32 v131, v145, v13
	v_sub_u32_e32 v2, v2, v10
	v_and_b32_e32 v10, 0x7ffffff3, v9
	v_lshlrev_b32_e32 v13, 2, v9
	v_mul_lo_u32 v2, v2, s74
	v_and_b32_e32 v13, 16, v13
	v_lshlrev_b32_e32 v10, 1, v10
	v_add3_u32 v2, v2, v13, v10
	v_and_or_b32 v146, v9, 8, v2
	v_mul_hi_i32 v2, v34, s79
	v_lshrrev_b32_e32 v9, 31, v2
	v_ashrrev_i32_e32 v2, 4, v2
	v_add_u32_e32 v2, v2, v9
	v_mul_lo_u32 v9, v2, s75
	v_sub_u32_e32 v9, v34, v9
	v_and_b32_e32 v10, 0x7ffffff3, v2
	v_lshlrev_b32_e32 v13, 2, v2
	v_mul_lo_u32 v9, v9, s74
	v_and_b32_e32 v13, 16, v13
	v_lshlrev_b32_e32 v10, 1, v10
	v_add3_u32 v9, v9, v13, v10
	v_and_or_b32 v148, v2, 8, v9
	v_mul_hi_i32 v2, v35, s79
	v_lshrrev_b32_e32 v9, 31, v2
	v_ashrrev_i32_e32 v2, 4, v2
	v_add_u32_e32 v2, v2, v9
	v_mul_lo_u32 v9, v2, s75
	v_sub_u32_e32 v9, v35, v9
	v_and_b32_e32 v10, 0x7ffffff3, v2
	v_lshlrev_b32_e32 v13, 2, v2
	v_mul_lo_u32 v9, v9, s74
	v_and_b32_e32 v13, 16, v13
	v_lshlrev_b32_e32 v10, 1, v10
	v_add3_u32 v9, v9, v13, v10
	v_and_or_b32 v149, v2, 8, v9
	v_mul_hi_i32 v2, v36, s79
	v_lshrrev_b32_e32 v9, 31, v2
	v_ashrrev_i32_e32 v2, 4, v2
	v_add_u32_e32 v2, v2, v9
	v_mul_lo_u32 v9, v2, s75
	v_sub_u32_e32 v9, v36, v9
	v_and_b32_e32 v10, 0x7ffffff3, v2
	v_lshlrev_b32_e32 v13, 2, v2
	v_mul_lo_u32 v9, v9, s74
	v_and_b32_e32 v13, 16, v13
	v_lshlrev_b32_e32 v10, 1, v10
	v_add3_u32 v9, v9, v13, v10
	v_and_or_b32 v150, v2, 8, v9
	v_mul_hi_i32 v2, v37, s79
	v_lshrrev_b32_e32 v9, 31, v2
	v_ashrrev_i32_e32 v2, 4, v2
	v_add_u32_e32 v2, v2, v9
	v_mul_lo_u32 v9, v2, s75
	v_sub_u32_e32 v9, v37, v9
	v_and_b32_e32 v10, 0x7ffffff3, v2
	v_lshlrev_b32_e32 v13, 2, v2
	v_mul_lo_u32 v9, v9, s74
	v_and_b32_e32 v13, 16, v13
	v_lshlrev_b32_e32 v10, 1, v10
	v_add3_u32 v9, v9, v13, v10
	v_and_or_b32 v151, v2, 8, v9
	v_mul_hi_i32 v2, v38, s79
	v_lshrrev_b32_e32 v9, 31, v2
	v_ashrrev_i32_e32 v2, 4, v2
	v_add_u32_e32 v2, v2, v9
	v_mul_lo_u32 v9, v2, s75
	v_sub_u32_e32 v9, v38, v9
	v_and_b32_e32 v10, 0x7ffffff3, v2
	v_lshlrev_b32_e32 v13, 2, v2
	v_mul_lo_u32 v9, v9, s74
	v_and_b32_e32 v13, 16, v13
	v_lshlrev_b32_e32 v10, 1, v10
	v_add3_u32 v9, v9, v13, v10
	v_and_or_b32 v152, v2, 8, v9
	v_mul_hi_i32 v2, v39, s79
	v_lshrrev_b32_e32 v9, 31, v2
	v_ashrrev_i32_e32 v2, 4, v2
	v_add_u32_e32 v2, v2, v9
	v_mul_lo_u32 v9, v2, s75
	v_sub_u32_e32 v9, v39, v9
	v_and_b32_e32 v10, 0x7ffffff3, v2
	v_lshlrev_b32_e32 v13, 2, v2
	v_mul_lo_u32 v9, v9, s74
	v_and_b32_e32 v13, 16, v13
	v_lshlrev_b32_e32 v10, 1, v10
	v_add3_u32 v9, v9, v13, v10
	v_and_or_b32 v153, v2, 8, v9
	v_mul_hi_i32 v2, v40, s79
	v_lshrrev_b32_e32 v9, 31, v2
	v_ashrrev_i32_e32 v2, 4, v2
	v_add_u32_e32 v2, v2, v9
	v_mul_lo_u32 v9, v2, s75
	v_sub_u32_e32 v9, v40, v9
	v_and_b32_e32 v10, 0x7ffffff3, v2
	v_lshlrev_b32_e32 v13, 2, v2
	v_mul_lo_u32 v9, v9, s74
	v_and_b32_e32 v13, 16, v13
	v_lshlrev_b32_e32 v10, 1, v10
	v_add3_u32 v9, v9, v13, v10
	v_and_or_b32 v154, v2, 8, v9
	v_mul_hi_i32 v2, v16, s79
	v_lshrrev_b32_e32 v9, 31, v2
	v_ashrrev_i32_e32 v2, 4, v2
	v_add_u32_e32 v2, v2, v9
	v_mul_lo_u32 v9, v2, s75
	v_sub_u32_e32 v9, v16, v9
	v_and_b32_e32 v10, 0x7ffffff3, v2
	v_lshlrev_b32_e32 v13, 2, v2
	v_mul_lo_u32 v9, v9, s74
	v_and_b32_e32 v13, 16, v13
	v_lshlrev_b32_e32 v10, 1, v10
	v_add3_u32 v9, v9, v13, v10
	v_and_or_b32 v155, v2, 8, v9
	v_mul_hi_i32 v2, v17, s79
	v_lshrrev_b32_e32 v9, 31, v2
	v_ashrrev_i32_e32 v2, 4, v2
	v_add_u32_e32 v2, v2, v9
	v_mul_lo_u32 v9, v2, s75
	v_sub_u32_e32 v9, v17, v9
	v_and_b32_e32 v10, 0x7ffffff3, v2
	v_lshlrev_b32_e32 v13, 2, v2
	v_mul_lo_u32 v9, v9, s74
	v_and_b32_e32 v13, 16, v13
	v_lshlrev_b32_e32 v10, 1, v10
	v_add3_u32 v9, v9, v13, v10
	v_and_or_b32 v156, v2, 8, v9
	v_mul_hi_i32 v2, v18, s79
	v_lshrrev_b32_e32 v9, 31, v2
	v_ashrrev_i32_e32 v2, 4, v2
	v_add_u32_e32 v2, v2, v9
	v_mul_lo_u32 v9, v2, s75
	v_sub_u32_e32 v9, v18, v9
	v_and_b32_e32 v10, 0x7ffffff3, v2
	v_lshlrev_b32_e32 v13, 2, v2
	v_mul_lo_u32 v9, v9, s74
	v_and_b32_e32 v13, 16, v13
	v_lshlrev_b32_e32 v10, 1, v10
	v_add3_u32 v9, v9, v13, v10
	v_and_or_b32 v157, v2, 8, v9
	v_mul_hi_i32 v2, v19, s79
	v_lshrrev_b32_e32 v9, 31, v2
	v_ashrrev_i32_e32 v2, 4, v2
	v_add_u32_e32 v2, v2, v9
	v_mul_lo_u32 v9, v2, s75
	v_sub_u32_e32 v9, v19, v9
	v_and_b32_e32 v10, 0x7ffffff3, v2
	v_lshlrev_b32_e32 v13, 2, v2
	v_mul_lo_u32 v9, v9, s74
	v_and_b32_e32 v13, 16, v13
	v_lshlrev_b32_e32 v10, 1, v10
	v_add3_u32 v9, v9, v13, v10
	s_movk_i32 s5, 0x1c0
	v_and_or_b32 v158, v2, 8, v9
	v_mul_lo_u32 v2, v8, s5
	v_add_lshl_u32 v159, v2, v0, 1
	v_lshl_add_u32 v160, v2, 1, v3
	v_lshlrev_b32_e32 v2, 4, v8
	v_lshlrev_b32_e32 v141, 9, v8
	v_and_b32_e32 v2, 0xffffffe0, v2
	v_and_b32_e32 v8, 8, v25
	s_mov_b32 s5, 0x7ffffff1
	v_add3_u32 v161, v12, v2, v8
	v_or_b32_e32 v2, 1, v25
	v_bitop3_b32 v9, v25, s5, 1 bitop3:0xc8
	v_mul_lo_u32 v2, v2, 56
	v_lshlrev_b32_e32 v9, 1, v9
	v_add3_u32 v164, v12, v9, v8
	v_add_u32_e32 v9, 56, v2
	s_mov_b32 s5, 0x7ffffff2
	v_add_lshl_u32 v165, v9, v0, 1
	v_lshl_add_u32 v166, v9, 1, v3
	v_bitop3_b32 v9, v25, s5, 2 bitop3:0xc8
	v_lshlrev_b32_e32 v9, 1, v9
	v_add3_u32 v167, v12, v9, v8
	v_add_u32_e32 v9, 0x70, v2
	s_mov_b32 s5, 0x7ffffff3
	v_add_lshl_u32 v168, v9, v0, 1
	v_lshl_add_u32 v169, v9, 1, v3
	v_bitop3_b32 v9, v25, s5, 3 bitop3:0xc8
	v_lshlrev_b32_e32 v9, 1, v9
	v_add3_u32 v170, v12, v9, v8
	v_add_u32_e32 v8, 0xe0, v2
	v_lshlrev_b32_e32 v11, 2, v11
	v_add_lshl_u32 v162, v2, v0, 1
	v_lshl_add_u32 v163, v2, 1, v3
	v_add_lshl_u32 v171, v8, v0, 1
	v_lshl_add_u32 v172, v8, 1, v3
	v_add_u32_e32 v8, 0x118, v2
	v_add_u32_e32 v2, 0x150, v2
	v_add_lshl_u32 v173, v8, v0, 1
	v_add_lshl_u32 v175, v2, v0, 1
	v_or_b32_e32 v0, 2, v11
	v_cmp_gt_u32_e64 s[22:23], v0, v1
	v_or_b32_e32 v0, 3, v11
	v_cmp_gt_u32_e64 s[24:25], v0, v1
	v_or_b32_e32 v0, 8, v11
	v_cmp_gt_u32_e64 s[26:27], v0, v1
	v_or_b32_e32 v0, 9, v11
	v_cmp_gt_u32_e64 s[28:29], v0, v1
	v_or_b32_e32 v0, 10, v11
	v_cmp_gt_u32_e64 s[30:31], v0, v1
	v_or_b32_e32 v0, 11, v11
	v_cmp_gt_u32_e64 s[34:35], v0, v1
	v_or_b32_e32 v0, 16, v11
	v_cmp_gt_u32_e64 s[36:37], v0, v1
	v_or_b32_e32 v0, 17, v11
	v_cmp_gt_u32_e64 s[38:39], v0, v1
	v_or_b32_e32 v0, 18, v11
	v_cmp_gt_u32_e64 s[40:41], v0, v1
	v_or_b32_e32 v0, 19, v11
	v_cmp_gt_u32_e64 s[42:43], v0, v1
	v_or_b32_e32 v0, 24, v11
	v_cmp_gt_u32_e64 s[44:45], v0, v1
	v_or_b32_e32 v0, 25, v11
	v_cmp_gt_u32_e64 s[46:47], v0, v1
	v_or_b32_e32 v0, 26, v11
	v_cmp_gt_u32_e64 s[48:49], v0, v1
	v_or_b32_e32 v0, 27, v11
	v_lshl_add_u32 v180, v2, 1, v3
	v_cmp_gt_u32_e64 s[50:51], v0, v1
	s_mul_hi_i32 s5, s54, 0x300000
	s_mul_i32 s54, s54, 0x300000
	v_mul_hi_u32_u24_e32 v0, 0x600, v1
	v_mul_u32_u24_e32 v2, 0x600, v1
	v_cmp_gt_u32_e64 s[18:19], v11, v1
	v_cmp_lt_u32_e64 s[20:21], v11, v1
	v_or_b32_e32 v1, s5, v0
	v_or_b32_e32 v0, s54, v2
	v_mad_u64_u32 v[0:1], s[4:5], s4, v231, v[0:1]
	v_ashrrev_i32_e32 v7, 31, v6
	v_or_b32_e32 v0, v0, v128
	v_lshl_add_u64 v[0:1], v[6:7], 2, v[0:1]
	v_lshl_add_u64 v[0:1], s[2:3], 0, v[0:1]
	s_mov_b64 s[2:3], 0x26e22140
	v_mov_b32_e32 v14, v179
	v_mov_b32_e32 v15, v179
	v_cmp_gt_i32_e32 vcc, 3, v24
	v_lshl_add_u32 v174, v8, 1, v3
	s_waitcnt vmcnt(27)
	v_perm_b32 v39, v27, v26, s76
	s_waitcnt vmcnt(23)
	v_perm_b32 v38, v29, v28, s76
	s_waitcnt vmcnt(19)
	v_perm_b32 v37, v31, v30, s76
	v_lshl_add_u64 v[132:133], s[56:57], 0, v[4:5]
	v_lshl_add_u64 v[134:135], v[0:1], 0, s[2:3]
	v_mov_b32_e32 v0, v179
	v_mov_b32_e32 v1, v179
	v_mov_b32_e32 v2, v179
	v_mov_b32_e32 v3, v179
	v_mov_b32_e32 v4, v179
	v_mov_b32_e32 v5, v179
	v_mov_b32_e32 v6, v179
	v_mov_b32_e32 v7, v179
	v_mov_b32_e32 v8, v179
	v_mov_b32_e32 v9, v179
	v_mov_b32_e32 v10, v179
	v_mov_b32_e32 v11, v179
	v_mov_b32_e32 v12, v179
	v_mov_b32_e32 v13, v179
	v_mov_b64_e32 v[30:31], v[14:15]
	s_waitcnt vmcnt(15)
	v_perm_b32 v36, v33, v32, s76
	s_mov_b32 s56, 32
	v_mov_b64_e32 v[28:29], v[12:13]
	v_mov_b64_e32 v[26:27], v[10:11]
	v_mov_b64_e32 v[24:25], v[8:9]
	v_mov_b64_e32 v[22:23], v[6:7]
	v_mov_b64_e32 v[20:21], v[4:5]
	v_mov_b64_e32 v[18:19], v[2:3]
	v_mov_b64_e32 v[16:17], v[0:1]
	v_lshlrev_b32_e32 v73, 1, v72
	v_lshlrev_b32_e32 v75, 1, v74
	v_lshlrev_b32_e32 v77, 1, v76
	v_lshlrev_b32_e32 v79, 1, v78
	v_lshlrev_b32_e32 v81, 1, v80
	v_lshlrev_b32_e32 v83, 1, v82
	v_lshlrev_b32_e32 v85, 1, v84
	v_lshlrev_b32_e32 v87, 1, v86
	v_lshlrev_b32_e32 v89, 1, v88
	v_lshlrev_b32_e32 v91, 1, v90
	v_lshlrev_b32_e32 v93, 1, v92
	v_lshlrev_b32_e32 v95, 1, v94
	v_lshlrev_b32_e32 v97, 1, v96
	v_lshlrev_b32_e32 v99, 1, v98
	v_lshlrev_b32_e32 v101, 1, v100
	v_lshlrev_b32_e32 v103, 1, v102
	v_lshlrev_b32_e32 v105, 1, v104
	v_lshlrev_b32_e32 v107, 1, v106
	v_lshlrev_b32_e32 v109, 1, v108
	v_lshlrev_b32_e32 v111, 1, v110
	v_lshlrev_b32_e32 v113, 1, v112
	v_lshlrev_b32_e32 v115, 1, v114
	v_lshlrev_b32_e32 v117, 1, v116
	v_lshlrev_b32_e32 v119, 1, v118
	v_lshlrev_b32_e32 v121, 1, v120
	v_lshlrev_b32_e32 v123, 1, v122
	v_lshlrev_b32_e32 v125, 1, v124
	s_branch .LBB0_537

.LBB0_543:
	s_or_b64 exec, exec, s[2:3]
	s_cmpk_lg_i32 s56, 0x800
	s_cselect_b32 s2, s56, 0x7e0
	s_add_u32 s2, s52, s2
	s_addc_u32 s3, s53, 0
	s_mul_i32 s4, s3, 0x900
	s_mul_hi_u32 s5, s2, 0x900
	s_add_i32 s5, s5, s4
	s_mul_i32 s4, s2, 0x900
	s_add_u32 s54, s58, s4
	s_addc_u32 s55, s59, s5
	v_lshl_add_u64 v[32:33], v[178:179], 1, s[54:55]
	s_waitcnt lgkmcnt(0)
	s_barrier
	global_load_ushort v195, v[32:33], off
	global_load_ushort v143, v73, s[54:55]
	global_load_ushort v196, v75, s[54:55]
	global_load_ushort v140, v77, s[54:55]
	global_load_ushort v197, v79, s[54:55]
	global_load_ushort v136, v81, s[54:55]
	global_load_ushort v198, v83, s[54:55]
	global_load_ushort v138, v85, s[54:55]
	global_load_ushort v199, v87, s[54:55]
	global_load_ushort v144, v89, s[54:55]
	global_load_ushort v200, v91, s[54:55]
	global_load_ushort v142, v93, s[54:55]
	global_load_ushort v201, v95, s[54:55]
	global_load_ushort v137, v97, s[54:55]
	global_load_ushort v202, v99, s[54:55]
	global_load_ushort v139, v101, s[54:55]
	global_load_ushort v181, v103, s[54:55]
	global_load_ushort v182, v105, s[54:55]
	global_load_ushort v183, v107, s[54:55]
	global_load_ushort v184, v109, s[54:55]
	global_load_ushort v185, v111, s[54:55]
	global_load_ushort v186, v113, s[54:55]
	global_load_ushort v187, v115, s[54:55]
	global_load_ushort v188, v117, s[54:55]
	global_load_ushort v189, v119, s[54:55]
	global_load_ushort v190, v121, s[54:55]
	s_lshl_b64 s[2:3], s[2:3], 6
	global_load_ushort v191, v123, s[54:55]
	global_load_ushort v192, v125, s[54:55]
	v_lshl_add_u64 v[32:33], v[132:133], 0, s[2:3]
	global_load_dword v193, v[32:33], off
	global_load_dword v194, v[32:33], off offset:1024
	s_and_saveexec_b64 s[2:3], vcc
	s_cbranch_execz .LBB0_536
	ds_read_b128 v[32:35], v145 offset:7168
	ds_read_b128 v[36:39], v145
	ds_read_b128 v[48:51], v145 offset:32
	ds_read_b128 v[52:55], v145 offset:7200
	v_cvt_pk_bf16_f32 v208, v8, v9
	v_cvt_pk_bf16_f32 v209, v10, v11
	s_waitcnt lgkmcnt(2)
	v_mfma_f32_32x32x16_bf16 v[32:47], v[32:35], v[36:39], 0
	v_cvt_pk_bf16_f32 v210, v12, v13
	v_cvt_pk_bf16_f32 v211, v14, v15
	v_cvt_pk_bf16_f32 v212, v16, v17
	v_cvt_pk_bf16_f32 v213, v18, v19
	v_cvt_pk_bf16_f32 v214, v20, v21
	v_cvt_pk_bf16_f32 v215, v22, v23
	s_waitcnt lgkmcnt(0)
	v_mfma_f32_32x32x16_bf16 v[32:47], v[52:55], v[48:51], v[32:47]
	ds_read_b128 v[48:51], v145 offset:7232
	ds_read_b128 v[52:55], v145 offset:64
	s_waitcnt lgkmcnt(0)
	v_mfma_f32_32x32x16_bf16 v[32:47], v[48:51], v[52:55], v[32:47]
	ds_read_b128 v[52:55], v130 offset:15872
	ds_read_b128 v[48:51], v130 offset:15904
	ds_read_b128 v[236:239], v145 offset:3584
	s_nop 8
	v_cndmask_b32_e64 v32, v32, 0, s[18:19]
	v_cndmask_b32_e64 v33, 0, v33, s[20:21]
	v_cndmask_b32_e64 v34, v34, 0, s[22:23]
	v_cndmask_b32_e64 v35, v35, 0, s[24:25]
	v_cndmask_b32_e64 v36, v36, 0, s[26:27]
	v_cndmask_b32_e64 v37, v37, 0, s[28:29]
	v_cndmask_b32_e64 v38, v38, 0, s[30:31]
	v_cndmask_b32_e64 v39, v39, 0, s[34:35]
	v_cndmask_b32_e64 v40, v40, 0, s[36:37]
	v_cndmask_b32_e64 v41, v41, 0, s[38:39]
	v_cndmask_b32_e64 v42, v42, 0, s[40:41]
	v_cndmask_b32_e64 v43, v43, 0, s[42:43]
	v_cndmask_b32_e64 v44, v44, 0, s[44:45]
	v_cndmask_b32_e64 v45, v45, 0, s[46:47]
	v_cndmask_b32_e64 v46, v46, 0, s[48:49]
	v_cndmask_b32_e64 v47, v47, 0, s[50:51]
	v_cvt_pk_bf16_f32 v32, v32, v33
	v_cvt_pk_bf16_f32 v33, v34, v35
	v_cvt_pk_bf16_f32 v34, v36, v37
	v_cvt_pk_bf16_f32 v35, v38, v39
	v_cvt_pk_bf16_f32 v204, v40, v41
	v_cvt_pk_bf16_f32 v205, v42, v43
	v_cvt_pk_bf16_f32 v206, v44, v45
	v_cvt_pk_bf16_f32 v207, v46, v47
	s_waitcnt lgkmcnt(2)
	v_mfma_f32_32x32x16_bf16 v[32:47], v[52:55], v[32:35], 0
	s_waitcnt lgkmcnt(1)
	v_mfma_f32_32x32x16_bf16 v[32:47], v[48:51], v[204:207], v[32:47]
	v_cvt_pk_bf16_f32 v204, v0, v1
	v_cvt_pk_bf16_f32 v205, v2, v3
	v_cvt_pk_bf16_f32 v206, v4, v5
	v_cvt_pk_bf16_f32 v207, v6, v7
	s_waitcnt lgkmcnt(0)
	s_nop 0
	v_mfma_f32_32x32x16_bf16 v[32:47], v[204:207], v[236:239], v[32:47]
	ds_read_b128 v[204:207], v145 offset:3616
	s_waitcnt lgkmcnt(0)
	v_mfma_f32_32x32x16_bf16 v[32:47], v[208:211], v[204:207], v[32:47]
	ds_read_b128 v[204:207], v145 offset:3648
	s_waitcnt lgkmcnt(0)
	v_mfma_f32_32x32x16_bf16 v[32:47], v[212:215], v[204:207], v[32:47]
	s_nop 11
	global_store_dwordx4 v[134:135], v[32:35], off offset:-64
	global_store_dwordx4 v[134:135], v[36:39], off offset:-32
	global_store_dwordx4 v[134:135], v[40:43], off
	global_store_dwordx4 v[134:135], v[44:47], off offset:32
	ds_read_b128 v[32:35], v128 offset:23680
	ds_read_b128 v[36:39], v128 offset:23552
	ds_read_b128 v[40:43], v128 offset:23584
	ds_read_b128 v[44:47], v128 offset:23712
	ds_read_b128 v[204:207], v128 offset:23616
	ds_read_b128 v[208:211], v128 offset:23744
	ds_read_b128 v[212:215], v128 offset:23648
	ds_read_b128 v[236:239], v128 offset:23776
	s_waitcnt lgkmcnt(6)
	v_pk_mul_f32 v[2:3], v[2:3], v[38:39]
	v_pk_mul_f32 v[0:1], v[0:1], v[36:37]
	v_pk_mul_f32 v[18:19], v[18:19], v[34:35]
	v_pk_mul_f32 v[16:17], v[16:17], v[32:33]
	ds_read_b128 v[32:35], v131 offset:10752
	ds_read_b128 v[36:39], v131 offset:10784
	s_waitcnt lgkmcnt(3)
	v_pk_mul_f32 v[14:15], v[14:15], v[214:215]
	v_pk_mul_f32 v[10:11], v[10:11], v[206:207]
	v_pk_mul_f32 v[6:7], v[6:7], v[42:43]
	v_pk_mul_f32 v[12:13], v[12:13], v[212:213]
	v_pk_mul_f32 v[8:9], v[8:9], v[204:205]
	v_pk_mul_f32 v[4:5], v[4:5], v[40:41]
	s_waitcnt lgkmcnt(2)
	v_pk_mul_f32 v[30:31], v[30:31], v[238:239]
	v_pk_mul_f32 v[26:27], v[26:27], v[210:211]
	s_waitcnt lgkmcnt(1)
	v_mfma_f32_32x32x16_bf16 v[0:15], v[32:35], v[52:55], v[0:15]
	ds_read_b128 v[32:35], v131 offset:13312
	v_mul_f32_e64 v22, v22, v46
	v_mul_f32_e64 v23, v23, v47
	v_mul_f32_e64 v28, v28, v236
	v_mul_f32_e64 v29, v29, v237
	v_pk_mul_f32 v[24:25], v[24:25], v[208:209]
	v_pk_mul_f32 v[20:21], v[20:21], v[44:45]
	s_waitcnt lgkmcnt(0)
	s_nop 0
	v_mfma_f32_32x32x16_bf16 v[16:31], v[32:35], v[52:55], v[16:31]
	ds_read_b128 v[32:35], v131 offset:13344
	v_mfma_f32_32x32x16_bf16 v[0:15], v[36:39], v[48:51], v[0:15]
	s_waitcnt lgkmcnt(0)
	v_mfma_f32_32x32x16_bf16 v[16:31], v[32:35], v[48:51], v[16:31]
	s_branch .LBB0_536
